# attention loops: next tile's first K fragment reads issued right after the end-of-PV barrier, ahead of slot rotation, back-edge and loop-top SALU
# speedup vs baseline: 1.0044x; 1.0044x over previous
; #define KRD(A, B, d0) do { const int ad_ = (kc ^ ((d0) << 5)) + kbt; A = lds_rd128<0>(ad_); B = lds_rd128<8192>(ad_); } while (0)
; #define A_WAITBAR(N) asm volatile("s_waitcnt vmcnt(" #N ") lgkmcnt(0) ; A256BAR\n\ts_barrier" ::: "memory")
; #define DMA_K(t, sl) do { const char* b_ = Kb + (size_t)(t) * TSTRIDE; const unsigned d_ = RFL(kdst + (sl) * 16384); glds16(b_ + koff[0], d_); glds16(b_ + koff[1], d_ + 1024); } while (0)
; #define DMA_V(t, sl) do { const char* b_ = Vb + (size_t)(t) * TSTRIDE; const unsigned d_ = RFL(vdst + (sl) * 32768); glds16(b_ + voff[0], d_); glds16(b_ + voff[1], d_ + 1024); glds16(b_ + voff[2], d_ + 2048); glds16(b_ + voff[3], d_ + 3072); } while (0)
; #define RESC(a) do { if (__any((a) < 1.f)) { if (hi == 0) al_l[r32] = (a); asm volatile("s_waitcnt lgkmcnt(0)" ::: "memory"); \
;     _Pragma("unroll") for (int d = 0; d < 8; ++d) _Pragma("unroll") for (int r = 0; r < 16; ++r) o[d][r] *= al_l[crow(r, hi)]; } } while (0)
; __device__ __forceinline__ void qkt_pipe(f32x16& p0, f32x16& p1, int kbt, int kc, const bf16x8* qr, const f32x16& z) {
;     ...
;   KRD(a0, b0, 0); KRD(a1, b1, 1); KRD(a2, b2, 2); KRD(a3, b3, 3);
; template <int mode> ...
;     ...
;   for (int j = 0; j < NT; ++j) {
;     const bool more = j + 2 < NT;
;     if (more) DMA_K(j + 2, s2);
;     f32x16 p0, p1; bf16x8 pa0, pa1, pa2, pa3;
;     __builtin_amdgcn_s_setprio(2);
;     { f32x16 negm;
; #pragma unroll
;       for (int r = 0; r < 16; ++r) negm[r] = -m_reg;
;       qkt_pipe(p0, p1, kb0 + s0 * 16384, kc, qr, negm); }
;     const float alpha = softmax_rel(p0, p1, j == 0, m_reg, l_reg, pa0, pa1, pa2, pa3);
;     RESC(alpha);
;     __builtin_amdgcn_s_setprio(0);
;     if (more) A_WAITBAR(6); else A_WAITBAR(0);
;     if (more) DMA_V(j + 2, s2);
;     pv8(o, vb0 + s0 * 32768, pa0, pa1, pa2, pa3);
;     if (more) A_WAITBAR(6); else A_WAITBAR(0);
;     { const int t_ = s0; s0 = s1; s1 = s2; s2 = t_; }
.LBB0_367:
	s_add_i32 s10, s10, 1
	s_add_u32 s38, s38, 0x180000
	v_add_f32_e32 v128, v212, v227
	s_addc_u32 s39, s39, 0
	s_cmp_eq_u32 s74, s10
	v_fmac_f32_e32 v128, v225, v226
	s_cbranch_scc1 .LBB0_374
	s_setprio 2
	v_lshl_add_u32 v212, s29, 14, v199
	v_add_u32_e32 v144, v212, v213
	ds_read_b128 v[194:197], v144 offset:0
	ds_read_b128 v[226:229], v144 offset:0x2000
	v_xor_b32_e32 v144, 32, v213
	v_add_u32_e32 v144, v212, v144
	ds_read_b128 v[230:233], v144 offset:0
	ds_read_b128 v[234:237], v144 offset:0x2000
	v_xor_b32_e32 v144, 64, v213
	v_add_u32_e32 v144, v212, v144
	ds_read_b128 v[238:241], v144 offset:0
	ds_read_b128 v[242:245], v144 offset:0x2000
	v_xor_b32_e32 v144, 0x60, v213
	v_add_u32_e32 v144, v212, v144
	ds_read_b128 v[246:249], v144 offset:0
	ds_read_b128 v[214:217], v144 offset:0x2000
	s_mov_b32 s24, s29
	s_mov_b32 s29, s9
	s_mov_b32 s9, s11
	v_mov_b32_e32 v225, v128
	s_branch .LBB0_348

; #define KRD(A, B, d0) do { const int ad_ = (kc ^ ((d0) << 5)) + kbt; A = lds_rd128<0>(ad_); B = lds_rd128<8192>(ad_); } while (0)
; #define A_WAITBAR(N) asm volatile("s_waitcnt vmcnt(" #N ") lgkmcnt(0) ; A256BAR\n\ts_barrier" ::: "memory")
; #define DMA_K(t, sl) do { const char* b_ = Kb + (size_t)(t) * TSTRIDE; const unsigned d_ = RFL(kdst + (sl) * 16384); glds16(b_ + koff[0], d_); glds16(b_ + koff[1], d_ + 1024); } while (0)
; #define DMA_V(t, sl) do { const char* b_ = Vb + (size_t)(t) * TSTRIDE; const unsigned d_ = RFL(vdst + (sl) * 32768); glds16(b_ + voff[0], d_); glds16(b_ + voff[1], d_ + 1024); glds16(b_ + voff[2], d_ + 2048); glds16(b_ + voff[3], d_ + 3072); } while (0)
; #define RESC(a) do { if (__any((a) < 1.f)) { if (hi == 0) al_l[r32] = (a); asm volatile("s_waitcnt lgkmcnt(0)" ::: "memory"); \
;     _Pragma("unroll") for (int d = 0; d < 8; ++d) _Pragma("unroll") for (int r = 0; r < 16; ++r) o[d][r] *= al_l[crow(r, hi)]; } } while (0)
; __device__ __forceinline__ void qkt_pipe(f32x16& p0, f32x16& p1, int kbt, int kc, const bf16x8* qr, const f32x16& z) {
;     ...
;   KRD(a0, b0, 0); KRD(a1, b1, 1); KRD(a2, b2, 2); KRD(a3, b3, 3);
; template <int mode> ...
;     ...
;   for (int j = 0; j < NT; ++j) {
;     const bool more = j + 2 < NT;
;     if (more) DMA_K(j + 2, s2);
;     f32x16 p0, p1; bf16x8 pa0, pa1, pa2, pa3;
;     __builtin_amdgcn_s_setprio(2);
;     { f32x16 negm;
; #pragma unroll
;       for (int r = 0; r < 16; ++r) negm[r] = -m_reg;
;       qkt_pipe(p0, p1, kb0 + s0 * 16384, kc, qr, negm); }
;     const float alpha = softmax_rel(p0, p1, j == 0, m_reg, l_reg, pa0, pa1, pa2, pa3);
;     RESC(alpha);
;     __builtin_amdgcn_s_setprio(0);
;     if (more) A_WAITBAR(6); else A_WAITBAR(0);
;     if (more) DMA_V(j + 2, s2);
;     pv8(o, vb0 + s0 * 32768, pa0, pa1, pa2, pa3);
;     if (more) A_WAITBAR(6); else A_WAITBAR(0);
;     { const int t_ = s0; s0 = s1; s1 = s2; s2 = t_; }
.LBB0_400:
	s_add_i32 s9, s9, 1
	s_add_u32 s60, s60, 0x180000
	v_add_f32_e32 v128, v212, v230
	s_addc_u32 s61, s61, 0
	s_cmp_eq_u32 s74, s9
	v_fmac_f32_e32 v128, v228, v229
	s_cbranch_scc1 .LBB0_407
	s_setprio 2
	v_lshl_add_u32 v212, s8, 14, v201
	v_add_u32_e32 v144, v212, v225
	ds_read_b128 v[194:197], v144 offset:0
	ds_read_b128 v[214:217], v144 offset:0x2000
	v_xor_b32_e32 v144, 32, v225
	v_add_u32_e32 v144, v212, v144
	ds_read_b128 v[230:233], v144 offset:0
	ds_read_b128 v[234:237], v144 offset:0x2000
	v_xor_b32_e32 v144, 64, v225
	v_add_u32_e32 v144, v212, v144
	ds_read_b128 v[238:241], v144 offset:0
	ds_read_b128 v[242:245], v144 offset:0x2000
	v_xor_b32_e32 v144, 0x60, v225
	v_add_u32_e32 v144, v212, v144
	ds_read_b128 v[246:249], v144 offset:0
	ds_read_b128 v[220:223], v144 offset:0x2000
	s_mov_b32 s11, s8
	s_mov_b32 s8, s7
	s_mov_b32 s7, s10
	v_mov_b32_e32 v228, v128
	s_branch .LBB0_381
